# NSA window-branch loop: V frags preloaded, PV MFMAs interleaved with exp VALU (same as fox)
# speedup vs baseline: 1.1583x; 1.0003x over previous
; #define MFMA(a, b, c) __builtin_amdgcn_mfma_f32_32x32x16_f16(__builtin_bit_cast(h16x8, (a)), __builtin_bit_cast(h16x8, (b)), (c), 0, 0, 0)
; DI unsigned pk2(float a, float b) { f2_t v = {a, b}; bf2_t r = __builtin_convertvector(v, bf2_t); return __builtin_bit_cast(unsigned, r); }
; template <int MODE> ...
;     ...
;             float ps = 0.f;
; #pragma unroll
;             for (int i = 0; i < 16; ++i) {
;               sv[i] = __builtin_amdgcn_exp2f(sv[i] - mc);
;               ps += sv[i];
;             }
;             l[nb] += ps;
; #pragma unroll
;             for (int s2 = 0; s2 < 2; ++s2) {
;               const unsigned u0 = pk2(sv[8 * s2], sv[8 * s2 + 1]), u1 = pk2(sv[8 * s2 + 2], sv[8 * s2 + 3]);
;               const unsigned u2 = pk2(sv[8 * s2 + 4], sv[8 * s2 + 5]), u3 = pk2(sv[8 * s2 + 6], sv[8 * s2 + 7]);
;               const uint4 uu = make_uint4(u0, u1, u2, u3);
;               pk[nb][s2] = __builtin_bit_cast(bf16x8, uu);
;             }
;           }
;         }
;         if (MODE != M_CMP2) {
; #pragma unroll
;           for (int s2 = 0; s2 < 2; ++s2) {
; #pragma unroll
;             for (int db = 0; db < 2; ++db) {
;               const u16* vp = Vt + (kb * 32 + 16 * s2 + 4 * h + q4) * LDK + db * 32 + 16 * blk + 4 * p4;
;               const s16x4 lo = __builtin_amdgcn_ds_read_tr16_b64_v4i16((__attribute__((address_space(3))) s16x4*)(vp));
;               const s16x4 hi = __builtin_amdgcn_ds_read_tr16_b64_v4i16((__attribute__((address_space(3))) s16x4*)(vp + 8 * LDK));
;               const bf16x8 a = __builtin_shufflevector(lo, hi, 0, 1, 2, 3, 4, 5, 6, 7);
;               O[db][0] = MFMA(a, pk[0][s2], O[db][0]);
;               O[db][1] = MFMA(a, pk[1][s2], O[db][1]);
;             }
;           }
.LBB0_753:
	v_or_b32_e32 v244, s20, v184
	v_mad_u32_u24 v244, v244, s76, v189
	ds_read_b64_tr_b16 v[228:229], v244 offset:18432
	ds_read_b64_tr_b16 v[230:231], v244 offset:19584
	ds_read_b64_tr_b16 v[232:233], v244 offset:18496
	ds_read_b64_tr_b16 v[234:235], v244 offset:19648
	ds_read_b64_tr_b16 v[236:237], v244 offset:20736
	ds_read_b64_tr_b16 v[238:239], v244 offset:21888
	ds_read_b64_tr_b16 v[240:241], v244 offset:20800
	ds_read_b64_tr_b16 v[242:243], v244 offset:21952
	v_sub_f32_e32 v80, v80, v15
	v_exp_f32_e32 v80, v80
	v_sub_f32_e32 v81, v81, v15
	v_exp_f32_e32 v81, v81
	v_add_f32_e32 v245, 0, v80
	v_sub_f32_e32 v82, v82, v15
	v_exp_f32_e32 v82, v82
	v_add_f32_e32 v245, v81, v245
	v_sub_f32_e32 v83, v83, v15
	v_exp_f32_e32 v83, v83
	v_add_f32_e32 v245, v82, v245
	v_sub_f32_e32 v84, v84, v15
	v_exp_f32_e32 v84, v84
	v_add_f32_e32 v245, v83, v245
	v_sub_f32_e32 v85, v85, v15
	v_exp_f32_e32 v85, v85
	v_add_f32_e32 v245, v84, v245
	v_sub_f32_e32 v86, v86, v15
	v_exp_f32_e32 v86, v86
	v_add_f32_e32 v245, v85, v245
	v_sub_f32_e32 v87, v87, v15
	v_exp_f32_e32 v87, v87
	v_add_f32_e32 v245, v86, v245
	v_sub_f32_e32 v88, v88, v15
	v_exp_f32_e32 v88, v88
	v_add_f32_e32 v245, v87, v245
	v_sub_f32_e32 v89, v89, v15
	v_exp_f32_e32 v89, v89
	v_add_f32_e32 v245, v88, v245
	v_sub_f32_e32 v90, v90, v15
	v_exp_f32_e32 v90, v90
	v_add_f32_e32 v245, v89, v245
	v_sub_f32_e32 v91, v91, v15
	v_exp_f32_e32 v91, v91
	v_add_f32_e32 v245, v90, v245
	v_sub_f32_e32 v92, v92, v15
	v_exp_f32_e32 v92, v92
	v_add_f32_e32 v245, v91, v245
	v_sub_f32_e32 v93, v93, v15
	v_exp_f32_e32 v93, v93
	v_add_f32_e32 v245, v92, v245
	v_sub_f32_e32 v94, v94, v15
	v_exp_f32_e32 v94, v94
	v_add_f32_e32 v245, v93, v245
	v_sub_f32_e32 v95, v95, v15
	v_exp_f32_e32 v95, v95
	v_add_f32_e32 v245, v94, v245
	v_add_f32_e32 v245, v95, v245
	v_cvt_pk_f16_f32 v10, v80, v81
	v_cvt_pk_f16_f32 v11, v82, v83
	v_cvt_pk_f16_f32 v12, v84, v85
	v_cvt_pk_f16_f32 v13, v86, v87
	v_cvt_pk_f16_f32 v246, v88, v89
	v_cvt_pk_f16_f32 v247, v90, v91
	v_cvt_pk_f16_f32 v248, v92, v93
	v_cvt_pk_f16_f32 v249, v94, v95
	v_add_f32_e32 v14, v14, v245
	s_waitcnt lgkmcnt(6)
	v_mfma_f32_32x32x16_f16 v[64:79], v[228:231], v[10:13], v[64:79]
	v_sub_f32_e32 v96, v96, v188
	v_exp_f32_e32 v96, v96
	v_sub_f32_e32 v97, v97, v188
	v_exp_f32_e32 v97, v97
	v_add_f32_e32 v250, 0, v96
	v_sub_f32_e32 v98, v98, v188
	v_exp_f32_e32 v98, v98
	v_add_f32_e32 v250, v97, v250
	v_sub_f32_e32 v99, v99, v188
	s_waitcnt lgkmcnt(4)
	v_mfma_f32_32x32x16_f16 v[48:63], v[232:235], v[10:13], v[48:63]
	v_exp_f32_e32 v99, v99
	v_add_f32_e32 v250, v98, v250
	v_sub_f32_e32 v100, v100, v188
	v_exp_f32_e32 v100, v100
	v_add_f32_e32 v250, v99, v250
	v_sub_f32_e32 v101, v101, v188
	v_exp_f32_e32 v101, v101
	v_add_f32_e32 v250, v100, v250
	v_sub_f32_e32 v102, v102, v188
	s_waitcnt lgkmcnt(2)
	v_mfma_f32_32x32x16_f16 v[64:79], v[236:239], v[246:249], v[64:79]
	v_exp_f32_e32 v102, v102
	v_add_f32_e32 v250, v101, v250
	v_sub_f32_e32 v103, v103, v188
	v_exp_f32_e32 v103, v103
	v_add_f32_e32 v250, v102, v250
	v_cvt_pk_f16_f32 v2, v96, v97
	v_cvt_pk_f16_f32 v3, v98, v99
	v_cvt_pk_f16_f32 v4, v100, v101
	v_cvt_pk_f16_f32 v5, v102, v103
	s_waitcnt lgkmcnt(0)
	v_mfma_f32_32x32x16_f16 v[48:63], v[240:243], v[246:249], v[48:63]
	s_nop 1
	v_mfma_f32_32x32x16_f16 v[32:47], v[228:231], v[2:5], v[32:47]
	v_sub_f32_e32 v104, v104, v188
	v_exp_f32_e32 v104, v104
	v_add_f32_e32 v250, v103, v250
	v_sub_f32_e32 v105, v105, v188
	v_exp_f32_e32 v105, v105
	v_add_f32_e32 v250, v104, v250
	v_sub_f32_e32 v106, v106, v188
	v_exp_f32_e32 v106, v106
	v_add_f32_e32 v250, v105, v250
	v_mfma_f32_32x32x16_f16 v[16:31], v[232:235], v[2:5], v[16:31]
	v_sub_f32_e32 v107, v107, v188
	v_exp_f32_e32 v107, v107
	v_add_f32_e32 v250, v106, v250
	v_sub_f32_e32 v108, v108, v188
	v_exp_f32_e32 v108, v108
	v_add_f32_e32 v250, v107, v250
	v_sub_f32_e32 v109, v109, v188
	v_exp_f32_e32 v109, v109
	v_add_f32_e32 v250, v108, v250
	v_sub_f32_e32 v110, v110, v188
	v_exp_f32_e32 v110, v110
	v_add_f32_e32 v250, v109, v250
	v_sub_f32_e32 v111, v111, v188
	v_exp_f32_e32 v111, v111
	v_add_f32_e32 v250, v110, v250
	v_add_f32_e32 v250, v111, v250
	v_cvt_pk_f16_f32 v6, v104, v105
	v_cvt_pk_f16_f32 v7, v106, v107
	v_cvt_pk_f16_f32 v8, v108, v109
	v_cvt_pk_f16_f32 v9, v110, v111
	v_add_f32_e32 v164, v164, v250
	s_nop 1
	v_mfma_f32_32x32x16_f16 v[32:47], v[236:239], v[6:9], v[32:47]
	v_mfma_f32_32x32x16_f16 v[16:31], v[240:243], v[6:9], v[16:31]
	v_mov_b32_e32 v2, v14
